# RMSNorm S7 row loop software-pipelined over two rows (two renamed body copies, loads of the next rows in flight)
# speedup vs baseline: 1.0021x; 1.0021x over previous
.LBB0_1239:
	v_readfirstlane_b32 s17, v18
	s_lshl_b32 s32, s8, 1
	s_lshl_b64 s[36:37], s[46:47], 1
	global_load_dwordx4 v[22:25], v[20:21], off
	global_load_dwordx4 v[28:31], v[20:21], off offset:1024
	s_add_i32 s23, s17, s8
	s_cmp_lt_i32 s23, 0x8000
	s_cselect_b32 s30, s46, 0
	s_cselect_b32 s31, s47, 0
	v_lshl_add_u64 v[204:205], v[20:21], 0, s[30:31]
	global_load_dwordx4 v[222:225], v[204:205], off
	global_load_dwordx4 v[228:231], v[204:205], off offset:1024
	s_waitcnt vmcnt(2)
	s_branch .Lnorm_s7_a
.Lnorm_s7_loop:
	s_waitcnt vmcnt(4)
.Lnorm_s7_a:
	v_and_b32_e32 v41, 0xffff0000, v22
	v_lshlrev_b32_e32 v40, 16, v22
	v_mul_f32_e32 v0, v41, v41
	v_lshlrev_b32_e32 v42, 16, v23
	v_fmac_f32_e32 v0, v40, v40
	v_and_b32_e32 v43, 0xffff0000, v23
	v_fmac_f32_e32 v0, v42, v42
	v_lshlrev_b32_e32 v44, 16, v24
	v_fmac_f32_e32 v0, v43, v43
	v_and_b32_e32 v45, 0xffff0000, v24
	v_fmac_f32_e32 v0, v44, v44
	v_lshlrev_b32_e32 v46, 16, v25
	v_fmac_f32_e32 v0, v45, v45
	v_and_b32_e32 v47, 0xffff0000, v25
	v_fmac_f32_e32 v0, v46, v46
	v_fmac_f32_e32 v0, v47, v47
	v_lshlrev_b32_e32 v22, 16, v28
	v_and_b32_e32 v23, 0xffff0000, v28
	v_fmac_f32_e32 v0, v22, v22
	v_lshlrev_b32_e32 v24, 16, v29
	v_fmac_f32_e32 v0, v23, v23
	v_and_b32_e32 v26, 0xffff0000, v30
	v_and_b32_e32 v25, 0xffff0000, v29
	v_fmac_f32_e32 v0, v24, v24
	v_lshlrev_b32_e32 v29, 16, v30
	v_mov_b32_e32 v28, v26
	v_fmac_f32_e32 v0, v25, v25
	v_pk_mul_f32 v[48:49], v[28:29], v[28:29]
	v_and_b32_e32 v27, s0, v31
	v_add_f32_e32 v0, v49, v0
	v_add_f32_e32 v19, v48, v0
	v_and_b32_e32 v0, 0xffff0000, v31
	v_lshlrev_b32_e32 v31, 16, v31
	v_mov_b32_e32 v30, v0
	v_pk_mul_f32 v[48:49], v[30:31], v[30:31]
	v_pk_mov_b32 v[26:27], v[28:29], v[26:27] op_sel:[1,0]
	v_add_f32_e32 v19, v49, v19
	v_add_f32_e32 v19, v48, v19
	ds_bpermute_b32 v32, v33, v19
	v_pk_mov_b32 v[28:29], v[30:31], v[0:1] op_sel:[1,0]
	s_waitcnt lgkmcnt(0)
	v_add_f32_e32 v19, v19, v32
	ds_bpermute_b32 v32, v34, v19
	s_waitcnt lgkmcnt(0)
	v_add_f32_e32 v19, v19, v32
	ds_bpermute_b32 v32, v35, v19
	s_waitcnt lgkmcnt(0)
	v_add_f32_e32 v19, v19, v32
	ds_bpermute_b32 v32, v36, v19
	s_waitcnt lgkmcnt(0)
	v_add_f32_e32 v19, v19, v32
	ds_bpermute_b32 v32, v37, v19
	s_waitcnt lgkmcnt(0)
	v_add_f32_e32 v19, v19, v32
	ds_bpermute_b32 v32, v38, v19
	s_waitcnt lgkmcnt(0)
	v_add_f32_e32 v19, v19, v32
	v_fmamk_f32 v19, v19, 0x3a800000, v194
	v_cmp_gt_f32_e32 vcc, s76, v19
	v_mul_f32_e32 v32, 0x4b800000, v19
	s_nop 0
	v_cndmask_b32_e32 v19, v19, v32, vcc
	v_rsq_f32_e32 v19, v19
	s_nop 0
	v_mul_f32_e32 v32, 0x45800000, v19
	v_cndmask_b32_e32 v32, v19, v32, vcc
	v_pk_mul_f32 v[40:41], v[40:41], v[32:33] op_sel_hi:[1,0]
	v_pk_mul_f32 v[42:43], v[42:43], v[32:33] op_sel_hi:[1,0]
	v_pk_mul_f32 v[44:45], v[44:45], v[32:33] op_sel_hi:[1,0]
	v_pk_mul_f32 v[42:43], v[8:9], v[42:43]
	v_pk_mul_f32 v[40:41], v[6:7], v[40:41]
	v_pk_mul_f32 v[44:45], v[2:3], v[44:45]
	v_cvt_pk_bf16_f32 v40, v40, v41
	v_cvt_pk_bf16_f32 v41, v42, v43
	v_cvt_pk_bf16_f32 v42, v44, v45
	v_add_co_u32_e32 v44, vcc, s12, v20
	v_pk_mul_f32 v[22:23], v[22:23], v[32:33] op_sel_hi:[1,0]
	v_pk_mul_f32 v[24:25], v[24:25], v[32:33] op_sel_hi:[1,0]
	v_pk_mul_f32 v[26:27], v[32:33], v[26:27] op_sel_hi:[0,1]
	v_addc_co_u32_e32 v45, vcc, -1, v21, vcc
	v_pk_mul_f32 v[24:25], v[16:17], v[24:25]
	v_pk_mul_f32 v[22:23], v[14:15], v[22:23]
	v_pk_mul_f32 v[26:27], v[10:11], v[26:27]
	v_cvt_pk_bf16_f32 v22, v22, v23
	v_cvt_pk_bf16_f32 v23, v24, v25
	v_cvt_pk_bf16_f32 v24, v26, v27
	v_add_co_u32_e32 v26, vcc, 0xea67e000, v20
	v_pk_mul_f32 v[46:47], v[46:47], v[32:33] op_sel_hi:[1,0]
	v_pk_mul_f32 v[28:29], v[32:33], v[28:29] op_sel_hi:[0,1]
	v_addc_co_u32_e32 v27, vcc, -1, v21, vcc
	v_pk_mul_f32 v[46:47], v[4:5], v[46:47]
	v_pk_mul_f32 v[28:29], v[12:13], v[28:29]
	v_cvt_pk_bf16_f32 v43, v46, v47
	v_cvt_pk_bf16_f32 v25, v28, v29
	global_store_dwordx4 v[44:45], v[40:43], off
	global_store_dwordx4 v[26:27], v[22:25], off offset:-3072
	s_add_i32 s17, s17, s32
	s_cmp_lt_i32 s17, 0x8000
	s_cselect_b32 s30, s36, 0
	s_cselect_b32 s31, s37, 0
	v_lshl_add_u64 v[20:21], v[20:21], 0, s[30:31]
	global_load_dwordx4 v[22:25], v[20:21], off
	global_load_dwordx4 v[28:31], v[20:21], off offset:1024
	s_cmp_ge_i32 s23, 0x8000
	s_cbranch_scc1 .Lnorm_s7_done
	s_waitcnt vmcnt(4)
	v_and_b32_e32 v41, 0xffff0000, v222
	v_lshlrev_b32_e32 v40, 16, v222
	v_mul_f32_e32 v0, v41, v41
	v_lshlrev_b32_e32 v42, 16, v223
	v_fmac_f32_e32 v0, v40, v40
	v_and_b32_e32 v43, 0xffff0000, v223
	v_fmac_f32_e32 v0, v42, v42
	v_lshlrev_b32_e32 v44, 16, v224
	v_fmac_f32_e32 v0, v43, v43
	v_and_b32_e32 v45, 0xffff0000, v224
	v_fmac_f32_e32 v0, v44, v44
	v_lshlrev_b32_e32 v46, 16, v225
	v_fmac_f32_e32 v0, v45, v45
	v_and_b32_e32 v47, 0xffff0000, v225
	v_fmac_f32_e32 v0, v46, v46
	v_fmac_f32_e32 v0, v47, v47
	v_lshlrev_b32_e32 v222, 16, v228
	v_and_b32_e32 v223, 0xffff0000, v228
	v_fmac_f32_e32 v0, v222, v222
	v_lshlrev_b32_e32 v224, 16, v229
	v_fmac_f32_e32 v0, v223, v223
	v_and_b32_e32 v226, 0xffff0000, v230
	v_and_b32_e32 v225, 0xffff0000, v229
	v_fmac_f32_e32 v0, v224, v224
	v_lshlrev_b32_e32 v229, 16, v230
	v_mov_b32_e32 v228, v226
	v_fmac_f32_e32 v0, v225, v225
	v_pk_mul_f32 v[48:49], v[228:229], v[228:229]
	v_and_b32_e32 v227, s0, v231
	v_add_f32_e32 v0, v49, v0
	v_add_f32_e32 v19, v48, v0
	v_and_b32_e32 v0, 0xffff0000, v231
	v_lshlrev_b32_e32 v231, 16, v231
	v_mov_b32_e32 v230, v0
	v_pk_mul_f32 v[48:49], v[230:231], v[230:231]
	v_pk_mov_b32 v[226:227], v[228:229], v[226:227] op_sel:[1,0]
	v_add_f32_e32 v19, v49, v19
	v_add_f32_e32 v19, v48, v19
	ds_bpermute_b32 v32, v33, v19
	v_pk_mov_b32 v[228:229], v[230:231], v[0:1] op_sel:[1,0]
	s_waitcnt lgkmcnt(0)
	v_add_f32_e32 v19, v19, v32
	ds_bpermute_b32 v32, v34, v19
	s_waitcnt lgkmcnt(0)
	v_add_f32_e32 v19, v19, v32
	ds_bpermute_b32 v32, v35, v19
	s_waitcnt lgkmcnt(0)
	v_add_f32_e32 v19, v19, v32
	ds_bpermute_b32 v32, v36, v19
	s_waitcnt lgkmcnt(0)
	v_add_f32_e32 v19, v19, v32
	ds_bpermute_b32 v32, v37, v19
	s_waitcnt lgkmcnt(0)
	v_add_f32_e32 v19, v19, v32
	ds_bpermute_b32 v32, v38, v19
	s_waitcnt lgkmcnt(0)
	v_add_f32_e32 v19, v19, v32
	v_fmamk_f32 v19, v19, 0x3a800000, v194
	v_cmp_gt_f32_e32 vcc, s76, v19
	v_mul_f32_e32 v32, 0x4b800000, v19
	s_nop 0
	v_cndmask_b32_e32 v19, v19, v32, vcc
	v_rsq_f32_e32 v19, v19
	s_nop 0
	v_mul_f32_e32 v32, 0x45800000, v19
	v_cndmask_b32_e32 v32, v19, v32, vcc
	v_pk_mul_f32 v[40:41], v[40:41], v[32:33] op_sel_hi:[1,0]
	v_pk_mul_f32 v[42:43], v[42:43], v[32:33] op_sel_hi:[1,0]
	v_pk_mul_f32 v[44:45], v[44:45], v[32:33] op_sel_hi:[1,0]
	v_pk_mul_f32 v[42:43], v[8:9], v[42:43]
	v_pk_mul_f32 v[40:41], v[6:7], v[40:41]
	v_pk_mul_f32 v[44:45], v[2:3], v[44:45]
	v_cvt_pk_bf16_f32 v40, v40, v41
	v_cvt_pk_bf16_f32 v41, v42, v43
	v_cvt_pk_bf16_f32 v42, v44, v45
	v_add_co_u32_e32 v44, vcc, s12, v204
	v_pk_mul_f32 v[222:223], v[222:223], v[32:33] op_sel_hi:[1,0]
	v_pk_mul_f32 v[224:225], v[224:225], v[32:33] op_sel_hi:[1,0]
	v_pk_mul_f32 v[226:227], v[32:33], v[226:227] op_sel_hi:[0,1]
	v_addc_co_u32_e32 v45, vcc, -1, v205, vcc
	v_pk_mul_f32 v[224:225], v[16:17], v[224:225]
	v_pk_mul_f32 v[222:223], v[14:15], v[222:223]
	v_pk_mul_f32 v[226:227], v[10:11], v[226:227]
	v_cvt_pk_bf16_f32 v222, v222, v223
	v_cvt_pk_bf16_f32 v223, v224, v225
	v_cvt_pk_bf16_f32 v224, v226, v227
	v_add_co_u32_e32 v226, vcc, 0xea67e000, v204
	v_pk_mul_f32 v[46:47], v[46:47], v[32:33] op_sel_hi:[1,0]
	v_pk_mul_f32 v[228:229], v[32:33], v[228:229] op_sel_hi:[0,1]
	v_addc_co_u32_e32 v227, vcc, -1, v205, vcc
	v_pk_mul_f32 v[46:47], v[4:5], v[46:47]
	v_pk_mul_f32 v[228:229], v[12:13], v[228:229]
	v_cvt_pk_bf16_f32 v43, v46, v47
	v_cvt_pk_bf16_f32 v225, v228, v229
	global_store_dwordx4 v[44:45], v[40:43], off
	global_store_dwordx4 v[226:227], v[222:225], off offset:-3072
	s_add_i32 s23, s23, s32
	s_cmp_lt_i32 s23, 0x8000
	s_cselect_b32 s30, s36, 0
	s_cselect_b32 s31, s37, 0
	v_lshl_add_u64 v[204:205], v[204:205], 0, s[30:31]
	global_load_dwordx4 v[222:225], v[204:205], off
	global_load_dwordx4 v[228:231], v[204:205], off offset:1024
	s_cmp_lt_i32 s17, 0x8000
	s_cbranch_scc1 .Lnorm_s7_loop
.Lnorm_s7_done:
.LBB0_1240:
	s_or_b64 exec, exec, s[0:1]
	s_waitcnt vmcnt(0)
	s_barrier
	s_and_saveexec_b64 s[0:1], s[84:85]
	s_cbranch_execz .LBB0_1292
	v_readlane_b32 s2, v254, 37
	s_waitcnt vmcnt(0) expcnt(0) lgkmcnt(0)
	s_nop 0
	v_mov_b32_e32 v0, s2
	ds_read_b32 v3, v0
	v_readlane_b32 s2, v254, 38
	s_waitcnt lgkmcnt(0)
	v_cmp_ne_u32_e32 vcc, 0, v3
	v_mov_b32_e32 v0, s2
	ds_read_b32 v2, v0
	s_cbranch_vccnz .LBB0_1256
	s_mov_b32 s2, 1
	s_branch .LBB0_1244
